# hyena gating: one workgroup barrier instead of two back-to-back before the gate-row staging
# speedup vs baseline: 1.0024x; 1.0024x over previous
.LBB0_1088:
	s_or_b64 exec, exec, s[12:13]
	s_and_b64 s[2:3], s[2:3], exec
	s_cselect_b32 s2, s54, 0x400
	s_barrier
	v_mbcnt_lo_u32_b32 v0, -1, 0
	v_mbcnt_hi_u32_b32 v0, -1, v0
	s_add_i32 s12, s2, s16
	s_lshl_b32 s2, s2, 2
	v_add_u32_e32 v4, s33, v0
	v_mov_b32_e32 v0, s2
	s_add_i32 s2, s12, 0x600
	s_ashr_i32 s3, s2, 31
	s_lshl_b64 s[2:3], s[2:3], 2
	s_add_u32 s2, s46, s2
	s_addc_u32 s3, s47, s3
	global_load_dword v10, v0, s[36:37]
	global_load_dword v9, v0, s[38:39]
	global_load_dword v8, v0, s[40:41]
	global_load_dword v12, v1, s[2:3]
	s_mov_b64 s[2:3], s[0:1]
	s_load_dwordx2 s[2:3], s[2:3], 0xb8
	v_and_b32_e32 v13, 1, v4
	v_or_b32_e32 v0, s31, v13
	v_ashrrev_i32_e32 v5, 6, v4
	s_waitcnt lgkmcnt(0)
	s_add_u32 s13, s2, s14
	s_addc_u32 s17, s3, s15
	s_lshl_b64 s[2:3], s[66:67], 2
	s_add_u32 s2, s13, s2
	s_addc_u32 s3, s17, s3
	s_add_u32 s2, s2, s26
	s_addc_u32 s3, s3, s27
	global_load_dword v11, v1, s[2:3]
	s_mul_i32 s2, s31, s87
	s_add_i32 s2, s2, s12
	s_ashr_i32 s3, s2, 31
	s_lshl_b64 s[2:3], s[2:3], 13
	s_add_u32 s2, s2, s18
	s_addc_u32 s3, s3, s19
	s_add_u32 s12, s2, 0xc00000
	s_addc_u32 s13, s3, 0
	v_lshlrev_b32_e32 v2, 4, v4
	global_load_dwordx4 v[32:35], v2, s[2:3]
	global_load_dwordx4 v[36:39], v2, s[12:13]
	v_lshrrev_b32_e32 v2, 5, v4
	v_and_b32_e32 v3, 31, v4
	v_mul_u32_u24_e32 v2, 0x210, v2
	v_lshl_add_u32 v2, v3, 4, v2
	v_lshlrev_b32_e32 v6, 7, v4
	v_and_b32_e32 v4, 32, v4
	s_movk_i32 s2, 0xf00
	v_and_or_b32 v4, v6, s2, v4
	v_add_u32_e32 v6, v5, v4
	v_mov_b32_e32 v14, s52
	s_movk_i32 s2, 0x2180
	v_mad_u32_u24 v13, v13, s2, v14
	v_lshrrev_b32_e32 v14, 8, v6
	v_lshlrev_b32_e32 v15, 1, v6
	v_and_b32_e32 v15, 0x1fe, v15
	v_mad_i32_i24 v14, v14, s53, v13
	v_add_u32_e32 v14, v14, v15
	v_lshlrev_b32_e32 v7, 12, v0
	v_subrev_u32_e32 v3, s52, v14
	v_mov_b32_e32 v5, 18
	v_and_b32_e32 v4, 0xff, v6
	v_cmp_eq_u32_e32 vcc, 0, v4
	v_add_u32_e32 v13, 0xd8, v6
	s_nop 0
	v_cndmask_b32_e32 v4, 2, v5, vcc
	v_cmp_eq_u32_e32 vcc, 0, v6
	v_and_b32_e32 v0, 0xff, v13
	s_nop 0
	v_cndmask_b32_e32 v4, v4, v1, vcc
	s_movk_i32 s2, 0xff
	v_cmp_eq_u32_e32 vcc, s2, v0
	v_sub_u32_e32 v4, v3, v4
	s_nop 0
	v_cndmask_b32_e32 v0, 2, v5, vcc
	v_cmp_eq_u32_e32 vcc, s85, v13
	s_nop 1
	v_cndmask_b32_e32 v0, v0, v1, vcc
	v_add_u32_e32 v5, v3, v0
	s_waitcnt vmcnt(0)
	ds_write_b128 v2, v[32:35]
	ds_write_b128 v2, v[36:39] offset:8576
	s_waitcnt lgkmcnt(0)
	s_barrier
	ds_read_u16 v32, v3
	ds_read_u16 v48, v4
	ds_read_u16 v64, v3 offset:2
	ds_read_u16 v33, v3 offset:16
	ds_read_u16 v49, v3 offset:14
	ds_read_u16 v65, v3 offset:18
	ds_read_u16 v34, v3 offset:32
	ds_read_u16 v50, v3 offset:30
	ds_read_u16 v66, v3 offset:34
	ds_read_u16 v35, v3 offset:48
	ds_read_u16 v51, v3 offset:46
	ds_read_u16 v67, v3 offset:50
	ds_read_u16 v36, v3 offset:128
	ds_read_u16 v52, v3 offset:126
	ds_read_u16 v68, v3 offset:130
	ds_read_u16 v37, v3 offset:144
	ds_read_u16 v53, v3 offset:142
	ds_read_u16 v69, v3 offset:146
	ds_read_u16 v38, v3 offset:160
	ds_read_u16 v54, v3 offset:158
	ds_read_u16 v70, v3 offset:162
	ds_read_u16 v39, v3 offset:176
	ds_read_u16 v55, v3 offset:174
	ds_read_u16 v71, v3 offset:178
	ds_read_u16 v40, v3 offset:256
	ds_read_u16 v56, v3 offset:254
	ds_read_u16 v72, v3 offset:258
	ds_read_u16 v41, v3 offset:272
	ds_read_u16 v57, v3 offset:270
	ds_read_u16 v73, v3 offset:274
	ds_read_u16 v42, v3 offset:288
	ds_read_u16 v58, v3 offset:286
	ds_read_u16 v74, v3 offset:290
	ds_read_u16 v43, v3 offset:304
	ds_read_u16 v59, v3 offset:302
	ds_read_u16 v75, v3 offset:306
	ds_read_u16 v44, v3 offset:384
	ds_read_u16 v60, v3 offset:382
	ds_read_u16 v76, v3 offset:386
	ds_read_u16 v45, v3 offset:400
	ds_read_u16 v61, v3 offset:398
	ds_read_u16 v77, v3 offset:402
	ds_read_u16 v46, v3 offset:416
	ds_read_u16 v62, v3 offset:414
	ds_read_u16 v78, v3 offset:418
	ds_read_u16 v47, v3 offset:432
	ds_read_u16 v63, v3 offset:430
	ds_read_u16 v79, v5 offset:432
	ds_read_u16 v80, v14
	ds_read_u16 v81, v14 offset:16
	ds_read_u16 v82, v14 offset:32
	ds_read_u16 v83, v14 offset:48
	ds_read_u16 v84, v14 offset:128
	ds_read_u16 v85, v14 offset:144
	ds_read_u16 v86, v14 offset:160
	ds_read_u16 v87, v14 offset:176
	ds_read_u16 v88, v14 offset:256
	ds_read_u16 v89, v14 offset:272
	ds_read_u16 v90, v14 offset:288
	ds_read_u16 v91, v14 offset:304
	ds_read_u16 v92, v14 offset:384
	ds_read_u16 v93, v14 offset:400
	ds_read_u16 v94, v14 offset:416
	ds_read_u16 v95, v14 offset:432
	v_add_u32_e32 v15, v6, v7
	v_lshlrev_b32_e32 v15, 12, v15
	v_cmp_lt_i32_e32 vcc, 0, v6
	s_waitcnt lgkmcnt(0)
	s_nop 1
	v_cndmask_b32_e32 v48, 0, v48, vcc
	v_cmp_gt_i32_e32 vcc, s85, v13
	s_nop 1
	v_cndmask_b32_e32 v79, 0, v79, vcc
	v_lshlrev_b32_e32 v32, 16, v32
	v_lshlrev_b32_e32 v48, 16, v48
	v_lshlrev_b32_e32 v64, 16, v64
	v_fma_f32 v32, v12, v32, v8
	v_fmac_f32_e32 v32, v10, v48
	v_fmac_f32_e32 v32, v9, v64
	v_lshlrev_b32_e32 v80, 16, v80
	v_fma_f32 v80, v11, v80, v16
	v_mul_f32_e32 v80, v80, v32
	v_cvt_pk_bf16_f32 v80, v80, v80
	v_lshlrev_b32_e32 v33, 16, v33
	v_lshlrev_b32_e32 v49, 16, v49
	v_lshlrev_b32_e32 v65, 16, v65
	v_fma_f32 v33, v12, v33, v8
	v_fmac_f32_e32 v33, v10, v49
	v_fmac_f32_e32 v33, v9, v65
	v_lshlrev_b32_e32 v81, 16, v81
	v_fma_f32 v81, v11, v81, v17
	v_mul_f32_e32 v81, v81, v33
	v_cvt_pk_bf16_f32 v81, v81, v81
	v_lshlrev_b32_e32 v34, 16, v34
	v_lshlrev_b32_e32 v50, 16, v50
	v_lshlrev_b32_e32 v66, 16, v66
	v_fma_f32 v34, v12, v34, v8
	v_fmac_f32_e32 v34, v10, v50
	v_fmac_f32_e32 v34, v9, v66
	v_lshlrev_b32_e32 v82, 16, v82
	v_fma_f32 v82, v11, v82, v18
	v_mul_f32_e32 v82, v82, v34
	v_cvt_pk_bf16_f32 v82, v82, v82
	v_lshlrev_b32_e32 v35, 16, v35
	v_lshlrev_b32_e32 v51, 16, v51
	v_lshlrev_b32_e32 v67, 16, v67
	v_fma_f32 v35, v12, v35, v8
	v_fmac_f32_e32 v35, v10, v51
	v_fmac_f32_e32 v35, v9, v67
	v_lshlrev_b32_e32 v83, 16, v83
	v_fma_f32 v83, v11, v83, v19
	v_mul_f32_e32 v83, v83, v35
	v_cvt_pk_bf16_f32 v83, v83, v83
	v_lshlrev_b32_e32 v36, 16, v36
	v_lshlrev_b32_e32 v52, 16, v52
	v_lshlrev_b32_e32 v68, 16, v68
	v_fma_f32 v36, v12, v36, v8
	v_fmac_f32_e32 v36, v10, v52
	v_fmac_f32_e32 v36, v9, v68
	v_lshlrev_b32_e32 v84, 16, v84
	v_fma_f32 v84, v11, v84, v20
	v_mul_f32_e32 v84, v84, v36
	v_cvt_pk_bf16_f32 v84, v84, v84
	v_lshlrev_b32_e32 v37, 16, v37
	v_lshlrev_b32_e32 v53, 16, v53
	v_lshlrev_b32_e32 v69, 16, v69
	v_fma_f32 v37, v12, v37, v8
	v_fmac_f32_e32 v37, v10, v53
	v_fmac_f32_e32 v37, v9, v69
	v_lshlrev_b32_e32 v85, 16, v85
	v_fma_f32 v85, v11, v85, v21
	v_mul_f32_e32 v85, v85, v37
	v_cvt_pk_bf16_f32 v85, v85, v85
	v_lshlrev_b32_e32 v38, 16, v38
	v_lshlrev_b32_e32 v54, 16, v54
	v_lshlrev_b32_e32 v70, 16, v70
	v_fma_f32 v38, v12, v38, v8
	v_fmac_f32_e32 v38, v10, v54
	v_fmac_f32_e32 v38, v9, v70
	v_lshlrev_b32_e32 v86, 16, v86
	v_fma_f32 v86, v11, v86, v22
	v_mul_f32_e32 v86, v86, v38
	v_cvt_pk_bf16_f32 v86, v86, v86
	v_lshlrev_b32_e32 v39, 16, v39
	v_lshlrev_b32_e32 v55, 16, v55
	v_lshlrev_b32_e32 v71, 16, v71
	v_fma_f32 v39, v12, v39, v8
	v_fmac_f32_e32 v39, v10, v55
	v_fmac_f32_e32 v39, v9, v71
	v_lshlrev_b32_e32 v87, 16, v87
	v_fma_f32 v87, v11, v87, v23
	v_mul_f32_e32 v87, v87, v39
	v_cvt_pk_bf16_f32 v87, v87, v87
	v_lshlrev_b32_e32 v40, 16, v40
	v_lshlrev_b32_e32 v56, 16, v56
	v_lshlrev_b32_e32 v72, 16, v72
	v_fma_f32 v40, v12, v40, v8
	v_fmac_f32_e32 v40, v10, v56
	v_fmac_f32_e32 v40, v9, v72
	v_lshlrev_b32_e32 v88, 16, v88
	v_fma_f32 v88, v11, v88, v24
	v_mul_f32_e32 v88, v88, v40
	v_cvt_pk_bf16_f32 v88, v88, v88
	v_lshlrev_b32_e32 v41, 16, v41
	v_lshlrev_b32_e32 v57, 16, v57
	v_lshlrev_b32_e32 v73, 16, v73
	v_fma_f32 v41, v12, v41, v8
	v_fmac_f32_e32 v41, v10, v57
	v_fmac_f32_e32 v41, v9, v73
	v_lshlrev_b32_e32 v89, 16, v89
	v_fma_f32 v89, v11, v89, v25
	v_mul_f32_e32 v89, v89, v41
	v_cvt_pk_bf16_f32 v89, v89, v89
	v_lshlrev_b32_e32 v42, 16, v42
	v_lshlrev_b32_e32 v58, 16, v58
	v_lshlrev_b32_e32 v74, 16, v74
	v_fma_f32 v42, v12, v42, v8
	v_fmac_f32_e32 v42, v10, v58
	v_fmac_f32_e32 v42, v9, v74
	v_lshlrev_b32_e32 v90, 16, v90
	v_fma_f32 v90, v11, v90, v26
	v_mul_f32_e32 v90, v90, v42
	v_cvt_pk_bf16_f32 v90, v90, v90
	v_lshlrev_b32_e32 v43, 16, v43
	v_lshlrev_b32_e32 v59, 16, v59
	v_lshlrev_b32_e32 v75, 16, v75
	v_fma_f32 v43, v12, v43, v8
	v_fmac_f32_e32 v43, v10, v59
	v_fmac_f32_e32 v43, v9, v75
	v_lshlrev_b32_e32 v91, 16, v91
	v_fma_f32 v91, v11, v91, v27
	v_mul_f32_e32 v91, v91, v43
	v_cvt_pk_bf16_f32 v91, v91, v91
	v_lshlrev_b32_e32 v44, 16, v44
	v_lshlrev_b32_e32 v60, 16, v60
	v_lshlrev_b32_e32 v76, 16, v76
	v_fma_f32 v44, v12, v44, v8
	v_fmac_f32_e32 v44, v10, v60
	v_fmac_f32_e32 v44, v9, v76
	v_lshlrev_b32_e32 v92, 16, v92
	v_fma_f32 v92, v11, v92, v28
	v_mul_f32_e32 v92, v92, v44
	v_cvt_pk_bf16_f32 v92, v92, v92
	v_lshlrev_b32_e32 v45, 16, v45
	v_lshlrev_b32_e32 v61, 16, v61
	v_lshlrev_b32_e32 v77, 16, v77
	v_fma_f32 v45, v12, v45, v8
	v_fmac_f32_e32 v45, v10, v61
	v_fmac_f32_e32 v45, v9, v77
	v_lshlrev_b32_e32 v93, 16, v93
	v_fma_f32 v93, v11, v93, v29
	v_mul_f32_e32 v93, v93, v45
	v_cvt_pk_bf16_f32 v93, v93, v93
	v_lshlrev_b32_e32 v46, 16, v46
	v_lshlrev_b32_e32 v62, 16, v62
	v_lshlrev_b32_e32 v78, 16, v78
	v_fma_f32 v46, v12, v46, v8
	v_fmac_f32_e32 v46, v10, v62
	v_fmac_f32_e32 v46, v9, v78
	v_lshlrev_b32_e32 v94, 16, v94
	v_fma_f32 v94, v11, v94, v30
	v_mul_f32_e32 v94, v94, v46
	v_cvt_pk_bf16_f32 v94, v94, v94
	v_lshlrev_b32_e32 v47, 16, v47
	v_lshlrev_b32_e32 v63, 16, v63
	v_lshlrev_b32_e32 v79, 16, v79
	v_fma_f32 v47, v12, v47, v8
	v_fmac_f32_e32 v47, v10, v63
	v_fmac_f32_e32 v47, v9, v79
	v_lshlrev_b32_e32 v95, 16, v95
	v_fma_f32 v95, v11, v95, v31
	v_mul_f32_e32 v95, v95, v47
	v_cvt_pk_bf16_f32 v95, v95, v95
	s_andn2_b64 s[12:13], exec, s[24:25]
	s_and_b64 vcc, exec, s[24:25]
	s_cbranch_vccnz .Lhy_gate_store
	ds_write_b16 v14, v80
	ds_write_b16 v14, v81 offset:16
	ds_write_b16 v14, v82 offset:32
	ds_write_b16 v14, v83 offset:48
	ds_write_b16 v14, v84 offset:128
	ds_write_b16 v14, v85 offset:144
	ds_write_b16 v14, v86 offset:160
	ds_write_b16 v14, v87 offset:176
	ds_write_b16 v14, v88 offset:256
	ds_write_b16 v14, v89 offset:272
	ds_write_b16 v14, v90 offset:288
	ds_write_b16 v14, v91 offset:304
	ds_write_b16 v14, v92 offset:384
	ds_write_b16 v14, v93 offset:400
	ds_write_b16 v14, v94 offset:416
	ds_write_b16 v14, v95 offset:432
	s_branch .LBB0_1070
